# combo11 + P1 bias items: the shift-table copy issues its 16 loads per thread in one trip instead of four drained trips
# speedup vs baseline: 1.0129x; 1.0044x over previous
; __device__ __forceinline__ void transpose_item(LAS unsigned char* lds, const TItem& it, int wv) {
;     ...
;     if (hb) {
;         for (int i = tid; i < NB * D; i += 512) shl[i] = it.shift[(size_t)(i >> 11) * MODS_LD + (i & 2047)];
;         __syncthreads();
;     }
.LBB0_119:
	v_ashrrev_i32_e32 v6, 11, v0
	v_ashrrev_i32_e32 v8, 11, v1
	v_and_b32_e32 v10, 0x7ff, v0
	v_add_u32_e32 v12, 0x400, v0
	v_mul_hi_i32_i24_e32 v7, 0x12000, v6
	v_mul_i32_i24_e32 v6, 0x12000, v6
	v_and_b32_e32 v14, 0x7ff, v1
	v_add_u32_e32 v11, 0x400, v1
	v_mul_hi_i32_i24_e32 v9, 0x12000, v8
	v_mul_i32_i24_e32 v8, 0x12000, v8
	v_lshlrev_b32_e32 v144, 2, v10
	v_ashrrev_i32_e32 v10, 11, v12
	v_lshl_add_u64 v[6:7], s[4:5], 0, v[6:7]
	v_ashrrev_i32_e32 v15, 11, v11
	v_and_b32_e32 v16, 0x7ff, v11
	v_and_b32_e32 v17, 0x7ff, v12
	v_lshl_add_u64 v[8:9], s[4:5], 0, v[8:9]
	v_mul_hi_i32_i24_e32 v11, 0x12000, v10
	v_mul_i32_i24_e32 v10, 0x12000, v10
	v_lshl_add_u64 v[6:7], v[6:7], 0, v[144:145]
	v_lshlrev_b32_e32 v144, 2, v14
	v_mul_hi_i32_i24_e32 v13, 0x12000, v15
	v_mul_i32_i24_e32 v12, 0x12000, v15
	v_lshl_add_u64 v[10:11], s[4:5], 0, v[10:11]
	v_lshl_add_u64 v[8:9], v[8:9], 0, v[144:145]
	v_lshlrev_b32_e32 v144, 2, v17
	v_lshl_add_u64 v[12:13], s[4:5], 0, v[12:13]
	global_load_dword v180, v[6:7], off
	global_load_dword v181, v[8:9], off
	v_lshl_add_u64 v[6:7], v[10:11], 0, v[144:145]
	v_lshlrev_b32_e32 v144, 2, v16
	v_lshl_add_u64 v[8:9], v[12:13], 0, v[144:145]
	global_load_dword v182, v[6:7], off
	s_nop 0
	global_load_dword v183, v[8:9], off
	v_add_u32_e32 v1, 0x800, v1
	v_add_u32_e32 v0, 0x800, v0
	v_ashrrev_i32_e32 v6, 11, v0
	v_ashrrev_i32_e32 v8, 11, v1
	v_and_b32_e32 v10, 0x7ff, v0
	v_add_u32_e32 v12, 0x400, v0
	v_mul_hi_i32_i24_e32 v7, 0x12000, v6
	v_mul_i32_i24_e32 v6, 0x12000, v6
	v_and_b32_e32 v14, 0x7ff, v1
	v_add_u32_e32 v11, 0x400, v1
	v_mul_hi_i32_i24_e32 v9, 0x12000, v8
	v_mul_i32_i24_e32 v8, 0x12000, v8
	v_lshlrev_b32_e32 v144, 2, v10
	v_ashrrev_i32_e32 v10, 11, v12
	v_lshl_add_u64 v[6:7], s[4:5], 0, v[6:7]
	v_ashrrev_i32_e32 v15, 11, v11
	v_and_b32_e32 v16, 0x7ff, v11
	v_and_b32_e32 v17, 0x7ff, v12
	v_lshl_add_u64 v[8:9], s[4:5], 0, v[8:9]
	v_mul_hi_i32_i24_e32 v11, 0x12000, v10
	v_mul_i32_i24_e32 v10, 0x12000, v10
	v_lshl_add_u64 v[6:7], v[6:7], 0, v[144:145]
	v_lshlrev_b32_e32 v144, 2, v14
	v_mul_hi_i32_i24_e32 v13, 0x12000, v15
	v_mul_i32_i24_e32 v12, 0x12000, v15
	v_lshl_add_u64 v[10:11], s[4:5], 0, v[10:11]
	v_lshl_add_u64 v[8:9], v[8:9], 0, v[144:145]
	v_lshlrev_b32_e32 v144, 2, v17
	v_lshl_add_u64 v[12:13], s[4:5], 0, v[12:13]
	global_load_dword v184, v[6:7], off
	global_load_dword v185, v[8:9], off
	v_lshl_add_u64 v[6:7], v[10:11], 0, v[144:145]
	v_lshlrev_b32_e32 v144, 2, v16
	v_lshl_add_u64 v[8:9], v[12:13], 0, v[144:145]
	global_load_dword v186, v[6:7], off
	s_nop 0
	global_load_dword v187, v[8:9], off
	v_add_u32_e32 v1, 0x800, v1
	v_add_u32_e32 v0, 0x800, v0
	v_ashrrev_i32_e32 v6, 11, v0
	v_ashrrev_i32_e32 v8, 11, v1
	v_and_b32_e32 v10, 0x7ff, v0
	v_add_u32_e32 v12, 0x400, v0
	v_mul_hi_i32_i24_e32 v7, 0x12000, v6
	v_mul_i32_i24_e32 v6, 0x12000, v6
	v_and_b32_e32 v14, 0x7ff, v1
	v_add_u32_e32 v11, 0x400, v1
	v_mul_hi_i32_i24_e32 v9, 0x12000, v8
	v_mul_i32_i24_e32 v8, 0x12000, v8
	v_lshlrev_b32_e32 v144, 2, v10
	v_ashrrev_i32_e32 v10, 11, v12
	v_lshl_add_u64 v[6:7], s[4:5], 0, v[6:7]
	v_ashrrev_i32_e32 v15, 11, v11
	v_and_b32_e32 v16, 0x7ff, v11
	v_and_b32_e32 v17, 0x7ff, v12
	v_lshl_add_u64 v[8:9], s[4:5], 0, v[8:9]
	v_mul_hi_i32_i24_e32 v11, 0x12000, v10
	v_mul_i32_i24_e32 v10, 0x12000, v10
	v_lshl_add_u64 v[6:7], v[6:7], 0, v[144:145]
	v_lshlrev_b32_e32 v144, 2, v14
	v_mul_hi_i32_i24_e32 v13, 0x12000, v15
	v_mul_i32_i24_e32 v12, 0x12000, v15
	v_lshl_add_u64 v[10:11], s[4:5], 0, v[10:11]
	v_lshl_add_u64 v[8:9], v[8:9], 0, v[144:145]
	v_lshlrev_b32_e32 v144, 2, v17
	v_lshl_add_u64 v[12:13], s[4:5], 0, v[12:13]
	global_load_dword v188, v[6:7], off
	global_load_dword v189, v[8:9], off
	v_lshl_add_u64 v[6:7], v[10:11], 0, v[144:145]
	v_lshlrev_b32_e32 v144, 2, v16
	v_lshl_add_u64 v[8:9], v[12:13], 0, v[144:145]
	global_load_dword v190, v[6:7], off
	s_nop 0
	global_load_dword v191, v[8:9], off
	v_add_u32_e32 v1, 0x800, v1
	v_add_u32_e32 v0, 0x800, v0
	v_ashrrev_i32_e32 v6, 11, v0
	v_ashrrev_i32_e32 v8, 11, v1
	v_and_b32_e32 v10, 0x7ff, v0
	v_add_u32_e32 v12, 0x400, v0
	v_mul_hi_i32_i24_e32 v7, 0x12000, v6
	v_mul_i32_i24_e32 v6, 0x12000, v6
	v_and_b32_e32 v14, 0x7ff, v1
	v_add_u32_e32 v11, 0x400, v1
	v_mul_hi_i32_i24_e32 v9, 0x12000, v8
	v_mul_i32_i24_e32 v8, 0x12000, v8
	v_lshlrev_b32_e32 v144, 2, v10
	v_ashrrev_i32_e32 v10, 11, v12
	v_lshl_add_u64 v[6:7], s[4:5], 0, v[6:7]
	v_ashrrev_i32_e32 v15, 11, v11
	v_and_b32_e32 v16, 0x7ff, v11
	v_and_b32_e32 v17, 0x7ff, v12
	v_lshl_add_u64 v[8:9], s[4:5], 0, v[8:9]
	v_mul_hi_i32_i24_e32 v11, 0x12000, v10
	v_mul_i32_i24_e32 v10, 0x12000, v10
	v_lshl_add_u64 v[6:7], v[6:7], 0, v[144:145]
	v_lshlrev_b32_e32 v144, 2, v14
	v_mul_hi_i32_i24_e32 v13, 0x12000, v15
	v_mul_i32_i24_e32 v12, 0x12000, v15
	v_lshl_add_u64 v[10:11], s[4:5], 0, v[10:11]
	v_lshl_add_u64 v[8:9], v[8:9], 0, v[144:145]
	v_lshlrev_b32_e32 v144, 2, v17
	v_lshl_add_u64 v[12:13], s[4:5], 0, v[12:13]
	global_load_dword v192, v[6:7], off
	global_load_dword v193, v[8:9], off
	v_lshl_add_u64 v[6:7], v[10:11], 0, v[144:145]
	v_lshlrev_b32_e32 v144, 2, v16
	v_lshl_add_u64 v[8:9], v[12:13], 0, v[144:145]
	global_load_dword v194, v[6:7], off
	s_nop 0
	global_load_dword v195, v[8:9], off
	v_add_u32_e32 v1, 0x800, v1
	v_add_u32_e32 v0, 0x800, v0
	v_add_u32_e32 v4, -8, v4
	v_add_u32_e32 v9, 0xffffe800, v5
	s_add_i32 s37, s37, 16
	v_cmp_eq_u32_e32 vcc, 0, v4
	v_mov_b32_e32 v6, s37
	s_or_b64 s[50:51], vcc, s[50:51]
	s_waitcnt vmcnt(0)
	ds_write_b32 v9, v180
	ds_write_b32 v9, v181 offset:2048
	ds_write_b32 v9, v182 offset:4096
	ds_write_b32 v9, v183 offset:6144
	ds_write_b32 v9, v184 offset:8192
	ds_write_b32 v9, v185 offset:10240
	ds_write_b32 v9, v186 offset:12288
	ds_write_b32 v9, v187 offset:14336
	ds_write_b32 v9, v188 offset:16384
	ds_write_b32 v9, v189 offset:18432
	ds_write_b32 v9, v190 offset:20480
	ds_write_b32 v9, v191 offset:22528
	ds_write_b32 v9, v192 offset:24576
	ds_write_b32 v9, v193 offset:26624
	ds_write_b32 v9, v194 offset:28672
	ds_write_b32 v9, v195 offset:30720
	v_add_u32_e32 v5, 0x8000, v5
	s_andn2_b64 exec, exec, s[50:51]
	s_cbranch_execnz .LBB0_119
	s_or_b64 exec, exec, s[50:51]
	v_lshlrev_b32_e32 v4, 9, v6
